# residual epilogue (out-proj layer>=1, down-proj): lane pairs exchange halves so each load/store covers whole 128-byte lines; 4 row groups of loads in flight
# speedup vs baseline: 1.0165x; 1.0050x over previous
;     ...
; #pragma unroll
;     for (int ai = 0; ai < 2; ++ai)
; #pragma unroll
;       for (int m = 0; m < 4; ++m)
;         epi(brow + ai * HALF + wr * 64 + m * 16 + fr, bcol + wc * 32, fq, acc[ai][0][m][0], acc[ai][0][m][1], acc[ai][1][m][0], acc[ai][1][m][1]);
.LBB0_1463:
	v_or_b32_e32 v0, s10, v218
	v_add_u32_e32 v136, v0, v215
	v_ashrrev_i32_e32 v137, 31, v136
	v_readlane_b32 s6, v253, 60
	v_lshl_or_b32 v0, v139, 5, s90
	v_lshlrev_b64 v[132:133], 12, v[136:137]
	v_readlane_b32 s7, v253, 61
	v_lshlrev_b64 v[134:135], 2, v[0:1]
	v_mov_b32_e32 v131, v1
	v_lshl_add_u64 v[132:133], s[6:7], 0, v[132:133]
	v_lshl_add_u64 v[132:133], v[132:133], 0, v[134:135]
	v_lshl_add_u64 v[132:133], v[132:133], 0, v[130:131]
	v_cndmask_b32_e64 v0, 0, 1, s[4:5]
	v_and_b32_e32 v134, 1, v210
	v_cmp_eq_u32_e32 vcc, 0, v134
	s_nop 1
	v_mov_b32_e32 v135, 0xfffff040
	v_cndmask_b32_e32 v134, v135, v1, vcc
	v_cndmask_b32_e32 v135, -1, v1, vcc
	v_lshl_add_u64 v[132:133], v[132:133], 0, v[134:135]
	s_mov_b64 s[6:7], 0x1000
	v_lshl_add_u64 v[136:137], v[132:133], 0, s[6:7]
	v_mov_b64_e32 v[138:139], v[132:133]
	v_mov_b64_e32 v[140:141], v[136:137]
	global_load_dwordx4 v[168:171], v[138:139], off
	global_load_dwordx4 v[172:175], v[140:141], off
	global_load_dwordx4 v[176:179], v[138:139], off offset:512
	global_load_dwordx4 v[180:183], v[140:141], off offset:512
	s_mov_b64 s[6:7], 0x10000
	v_lshl_add_u64 v[142:143], v[132:133], 0, s[6:7]
	v_lshl_add_u64 v[144:145], v[136:137], 0, s[6:7]
	global_load_dwordx4 v[184:187], v[142:143], off
	global_load_dwordx4 v[188:191], v[144:145], off
	global_load_dwordx4 v[192:195], v[142:143], off offset:512
	global_load_dwordx4 v[196:199], v[144:145], off offset:512
	s_mov_b64 s[6:7], 0x20000
	v_lshl_add_u64 v[146:147], v[132:133], 0, s[6:7]
	v_lshl_add_u64 v[148:149], v[136:137], 0, s[6:7]
	global_load_dwordx4 v[220:223], v[146:147], off
	global_load_dwordx4 v[224:227], v[148:149], off
	global_load_dwordx4 v[228:231], v[146:147], off offset:512
	global_load_dwordx4 v[232:235], v[148:149], off offset:512
	s_mov_b64 s[6:7], 0x30000
	v_lshl_add_u64 v[150:151], v[132:133], 0, s[6:7]
	v_lshl_add_u64 v[152:153], v[136:137], 0, s[6:7]
	global_load_dwordx4 v[236:239], v[150:151], off
	global_load_dwordx4 v[240:243], v[152:153], off
	global_load_dwordx4 v[244:247], v[150:151], off offset:512
	global_load_dwordx4 v[248:251], v[152:153], off offset:512
	v_mov_b32_dpp v200, v118 quad_perm:[1,0,3,2] row_mask:0xf bank_mask:0xf
	v_cndmask_b32_dpp v201, v114, v200, vcc quad_perm:[1,0,3,2] row_mask:0xf bank_mask:0xf
	v_cndmask_b32_e32 v118, v201, v118, vcc
	v_cndmask_b32_e32 v114, v114, v201, vcc
	v_mov_b32_dpp v200, v119 quad_perm:[1,0,3,2] row_mask:0xf bank_mask:0xf
	v_cndmask_b32_dpp v201, v115, v200, vcc quad_perm:[1,0,3,2] row_mask:0xf bank_mask:0xf
	v_cndmask_b32_e32 v119, v201, v119, vcc
	v_cndmask_b32_e32 v115, v115, v201, vcc
	v_mov_b32_dpp v200, v120 quad_perm:[1,0,3,2] row_mask:0xf bank_mask:0xf
	v_cndmask_b32_dpp v201, v116, v200, vcc quad_perm:[1,0,3,2] row_mask:0xf bank_mask:0xf
	v_cndmask_b32_e32 v120, v201, v120, vcc
	v_cndmask_b32_e32 v116, v116, v201, vcc
	v_mov_b32_dpp v200, v121 quad_perm:[1,0,3,2] row_mask:0xf bank_mask:0xf
	v_cndmask_b32_dpp v201, v117, v200, vcc quad_perm:[1,0,3,2] row_mask:0xf bank_mask:0xf
	v_cndmask_b32_e32 v121, v201, v121, vcc
	v_cndmask_b32_e32 v117, v117, v201, vcc
	v_mov_b32_dpp v200, v126 quad_perm:[1,0,3,2] row_mask:0xf bank_mask:0xf
	v_cndmask_b32_dpp v201, v122, v200, vcc quad_perm:[1,0,3,2] row_mask:0xf bank_mask:0xf
	v_cndmask_b32_e32 v126, v201, v126, vcc
	v_cndmask_b32_e32 v122, v122, v201, vcc
	v_mov_b32_dpp v200, v127 quad_perm:[1,0,3,2] row_mask:0xf bank_mask:0xf
	v_cndmask_b32_dpp v201, v123, v200, vcc quad_perm:[1,0,3,2] row_mask:0xf bank_mask:0xf
	v_cndmask_b32_e32 v127, v201, v127, vcc
	v_cndmask_b32_e32 v123, v123, v201, vcc
	v_mov_b32_dpp v200, v128 quad_perm:[1,0,3,2] row_mask:0xf bank_mask:0xf
	v_cndmask_b32_dpp v201, v124, v200, vcc quad_perm:[1,0,3,2] row_mask:0xf bank_mask:0xf
	v_cndmask_b32_e32 v128, v201, v128, vcc
	v_cndmask_b32_e32 v124, v124, v201, vcc
	v_mov_b32_dpp v200, v129 quad_perm:[1,0,3,2] row_mask:0xf bank_mask:0xf
	v_cndmask_b32_dpp v201, v125, v200, vcc quad_perm:[1,0,3,2] row_mask:0xf bank_mask:0xf
	v_cndmask_b32_e32 v129, v201, v129, vcc
	v_cndmask_b32_e32 v125, v125, v201, vcc
	s_waitcnt vmcnt(12)
	v_pk_add_f32 v[168:169], v[118:119], v[168:169]
	v_pk_add_f32 v[170:171], v[120:121], v[170:171]
	v_pk_add_f32 v[172:173], v[114:115], v[172:173]
	v_pk_add_f32 v[174:175], v[116:117], v[174:175]
	v_pk_add_f32 v[176:177], v[126:127], v[176:177]
	v_pk_add_f32 v[178:179], v[128:129], v[178:179]
	v_pk_add_f32 v[180:181], v[122:123], v[180:181]
	v_pk_add_f32 v[182:183], v[124:125], v[182:183]
	global_store_dwordx4 v[138:139], v[168:171], off
	global_store_dwordx4 v[140:141], v[172:175], off
	global_store_dwordx4 v[138:139], v[176:179], off offset:512
	global_store_dwordx4 v[140:141], v[180:183], off offset:512
	s_nop 1
	s_mov_b64 s[6:7], 0x80000
	v_lshl_add_u64 v[138:139], v[132:133], 0, s[6:7]
	v_lshl_add_u64 v[140:141], v[136:137], 0, s[6:7]
	global_load_dwordx4 v[168:171], v[138:139], off
	global_load_dwordx4 v[172:175], v[140:141], off
	global_load_dwordx4 v[176:179], v[138:139], off offset:512
	global_load_dwordx4 v[180:183], v[140:141], off offset:512
	v_mov_b32_dpp v200, v102 quad_perm:[1,0,3,2] row_mask:0xf bank_mask:0xf
	v_cndmask_b32_dpp v201, v98, v200, vcc quad_perm:[1,0,3,2] row_mask:0xf bank_mask:0xf
	v_cndmask_b32_e32 v102, v201, v102, vcc
	v_cndmask_b32_e32 v98, v98, v201, vcc
	v_mov_b32_dpp v200, v103 quad_perm:[1,0,3,2] row_mask:0xf bank_mask:0xf
	v_cndmask_b32_dpp v201, v99, v200, vcc quad_perm:[1,0,3,2] row_mask:0xf bank_mask:0xf
	v_cndmask_b32_e32 v103, v201, v103, vcc
	v_cndmask_b32_e32 v99, v99, v201, vcc
	v_mov_b32_dpp v200, v104 quad_perm:[1,0,3,2] row_mask:0xf bank_mask:0xf
	v_cndmask_b32_dpp v201, v100, v200, vcc quad_perm:[1,0,3,2] row_mask:0xf bank_mask:0xf
	v_cndmask_b32_e32 v104, v201, v104, vcc
	v_cndmask_b32_e32 v100, v100, v201, vcc
	v_mov_b32_dpp v200, v105 quad_perm:[1,0,3,2] row_mask:0xf bank_mask:0xf
	v_cndmask_b32_dpp v201, v101, v200, vcc quad_perm:[1,0,3,2] row_mask:0xf bank_mask:0xf
	v_cndmask_b32_e32 v105, v201, v105, vcc
	v_cndmask_b32_e32 v101, v101, v201, vcc
	v_mov_b32_dpp v200, v110 quad_perm:[1,0,3,2] row_mask:0xf bank_mask:0xf
	v_cndmask_b32_dpp v201, v106, v200, vcc quad_perm:[1,0,3,2] row_mask:0xf bank_mask:0xf
	v_cndmask_b32_e32 v110, v201, v110, vcc
	v_cndmask_b32_e32 v106, v106, v201, vcc
	v_mov_b32_dpp v200, v111 quad_perm:[1,0,3,2] row_mask:0xf bank_mask:0xf
	v_cndmask_b32_dpp v201, v107, v200, vcc quad_perm:[1,0,3,2] row_mask:0xf bank_mask:0xf
	v_cndmask_b32_e32 v111, v201, v111, vcc
	v_cndmask_b32_e32 v107, v107, v201, vcc
	v_mov_b32_dpp v200, v112 quad_perm:[1,0,3,2] row_mask:0xf bank_mask:0xf
	v_cndmask_b32_dpp v201, v108, v200, vcc quad_perm:[1,0,3,2] row_mask:0xf bank_mask:0xf
	v_cndmask_b32_e32 v112, v201, v112, vcc
	v_cndmask_b32_e32 v108, v108, v201, vcc
	v_mov_b32_dpp v200, v113 quad_perm:[1,0,3,2] row_mask:0xf bank_mask:0xf
	v_cndmask_b32_dpp v201, v109, v200, vcc quad_perm:[1,0,3,2] row_mask:0xf bank_mask:0xf
	v_cndmask_b32_e32 v113, v201, v113, vcc
	v_cndmask_b32_e32 v109, v109, v201, vcc
	s_waitcnt vmcnt(16)
;     ...
; #pragma unroll
;     for (int ai = 0; ai < 2; ++ai)
; #pragma unroll
;       for (int m = 0; m < 4; ++m)
;         epi(brow + ai * HALF + wr * 64 + m * 16 + fr, bcol + wc * 32, fq, acc[ai][0][m][0], acc[ai][0][m][1], acc[ai][1][m][0], acc[ai][1][m][1]);
	v_pk_add_f32 v[184:185], v[102:103], v[184:185]
	v_pk_add_f32 v[186:187], v[104:105], v[186:187]
	v_pk_add_f32 v[188:189], v[98:99], v[188:189]
	v_pk_add_f32 v[190:191], v[100:101], v[190:191]
	v_pk_add_f32 v[192:193], v[110:111], v[192:193]
	v_pk_add_f32 v[194:195], v[112:113], v[194:195]
	v_pk_add_f32 v[196:197], v[106:107], v[196:197]
	v_pk_add_f32 v[198:199], v[108:109], v[198:199]
	global_store_dwordx4 v[142:143], v[184:187], off
	global_store_dwordx4 v[144:145], v[188:191], off
	global_store_dwordx4 v[142:143], v[192:195], off offset:512
	global_store_dwordx4 v[144:145], v[196:199], off offset:512
	s_nop 1
	s_mov_b64 s[6:7], 0x90000
	v_lshl_add_u64 v[142:143], v[132:133], 0, s[6:7]
	v_lshl_add_u64 v[144:145], v[136:137], 0, s[6:7]
	global_load_dwordx4 v[184:187], v[142:143], off
	global_load_dwordx4 v[188:191], v[144:145], off
	global_load_dwordx4 v[192:195], v[142:143], off offset:512
	global_load_dwordx4 v[196:199], v[144:145], off offset:512
	v_mov_b32_dpp v200, v86 quad_perm:[1,0,3,2] row_mask:0xf bank_mask:0xf
	v_cndmask_b32_dpp v201, v82, v200, vcc quad_perm:[1,0,3,2] row_mask:0xf bank_mask:0xf
	v_cndmask_b32_e32 v86, v201, v86, vcc
	v_cndmask_b32_e32 v82, v82, v201, vcc
	v_mov_b32_dpp v200, v87 quad_perm:[1,0,3,2] row_mask:0xf bank_mask:0xf
	v_cndmask_b32_dpp v201, v83, v200, vcc quad_perm:[1,0,3,2] row_mask:0xf bank_mask:0xf
	v_cndmask_b32_e32 v87, v201, v87, vcc
	v_cndmask_b32_e32 v83, v83, v201, vcc
	v_mov_b32_dpp v200, v88 quad_perm:[1,0,3,2] row_mask:0xf bank_mask:0xf
	v_cndmask_b32_dpp v201, v84, v200, vcc quad_perm:[1,0,3,2] row_mask:0xf bank_mask:0xf
	v_cndmask_b32_e32 v88, v201, v88, vcc
	v_cndmask_b32_e32 v84, v84, v201, vcc
	v_mov_b32_dpp v200, v89 quad_perm:[1,0,3,2] row_mask:0xf bank_mask:0xf
	v_cndmask_b32_dpp v201, v85, v200, vcc quad_perm:[1,0,3,2] row_mask:0xf bank_mask:0xf
	v_cndmask_b32_e32 v89, v201, v89, vcc
	v_cndmask_b32_e32 v85, v85, v201, vcc
	v_mov_b32_dpp v200, v94 quad_perm:[1,0,3,2] row_mask:0xf bank_mask:0xf
	v_cndmask_b32_dpp v201, v90, v200, vcc quad_perm:[1,0,3,2] row_mask:0xf bank_mask:0xf
	v_cndmask_b32_e32 v94, v201, v94, vcc
	v_cndmask_b32_e32 v90, v90, v201, vcc
	v_mov_b32_dpp v200, v95 quad_perm:[1,0,3,2] row_mask:0xf bank_mask:0xf
	v_cndmask_b32_dpp v201, v91, v200, vcc quad_perm:[1,0,3,2] row_mask:0xf bank_mask:0xf
	v_cndmask_b32_e32 v95, v201, v95, vcc
	v_cndmask_b32_e32 v91, v91, v201, vcc
	v_mov_b32_dpp v200, v96 quad_perm:[1,0,3,2] row_mask:0xf bank_mask:0xf
	v_cndmask_b32_dpp v201, v92, v200, vcc quad_perm:[1,0,3,2] row_mask:0xf bank_mask:0xf
	v_cndmask_b32_e32 v96, v201, v96, vcc
	v_cndmask_b32_e32 v92, v92, v201, vcc
	v_mov_b32_dpp v200, v97 quad_perm:[1,0,3,2] row_mask:0xf bank_mask:0xf
	v_cndmask_b32_dpp v201, v93, v200, vcc quad_perm:[1,0,3,2] row_mask:0xf bank_mask:0xf
	v_cndmask_b32_e32 v97, v201, v97, vcc
	v_cndmask_b32_e32 v93, v93, v201, vcc
	s_waitcnt vmcnt(20)
	v_pk_add_f32 v[220:221], v[86:87], v[220:221]
	v_pk_add_f32 v[222:223], v[88:89], v[222:223]
	v_pk_add_f32 v[224:225], v[82:83], v[224:225]
	v_pk_add_f32 v[226:227], v[84:85], v[226:227]
	v_pk_add_f32 v[228:229], v[94:95], v[228:229]
	v_pk_add_f32 v[230:231], v[96:97], v[230:231]
	v_pk_add_f32 v[232:233], v[90:91], v[232:233]
	v_pk_add_f32 v[234:235], v[92:93], v[234:235]
	global_store_dwordx4 v[146:147], v[220:223], off
	global_store_dwordx4 v[148:149], v[224:227], off
	global_store_dwordx4 v[146:147], v[228:231], off offset:512
	global_store_dwordx4 v[148:149], v[232:235], off offset:512
	s_nop 1
	s_mov_b64 s[6:7], 0xa0000
	v_lshl_add_u64 v[146:147], v[132:133], 0, s[6:7]
	v_lshl_add_u64 v[148:149], v[136:137], 0, s[6:7]
	global_load_dwordx4 v[220:223], v[146:147], off
	global_load_dwordx4 v[224:227], v[148:149], off
	global_load_dwordx4 v[228:231], v[146:147], off offset:512
	global_load_dwordx4 v[232:235], v[148:149], off offset:512
	v_mov_b32_dpp v200, v70 quad_perm:[1,0,3,2] row_mask:0xf bank_mask:0xf
	v_cndmask_b32_dpp v201, v66, v200, vcc quad_perm:[1,0,3,2] row_mask:0xf bank_mask:0xf
	v_cndmask_b32_e32 v70, v201, v70, vcc
	v_cndmask_b32_e32 v66, v66, v201, vcc
	v_mov_b32_dpp v200, v71 quad_perm:[1,0,3,2] row_mask:0xf bank_mask:0xf
	v_cndmask_b32_dpp v201, v67, v200, vcc quad_perm:[1,0,3,2] row_mask:0xf bank_mask:0xf
	v_cndmask_b32_e32 v71, v201, v71, vcc
	v_cndmask_b32_e32 v67, v67, v201, vcc
	v_mov_b32_dpp v200, v72 quad_perm:[1,0,3,2] row_mask:0xf bank_mask:0xf
	v_cndmask_b32_dpp v201, v68, v200, vcc quad_perm:[1,0,3,2] row_mask:0xf bank_mask:0xf
	v_cndmask_b32_e32 v72, v201, v72, vcc
	v_cndmask_b32_e32 v68, v68, v201, vcc
	v_mov_b32_dpp v200, v73 quad_perm:[1,0,3,2] row_mask:0xf bank_mask:0xf
	v_cndmask_b32_dpp v201, v69, v200, vcc quad_perm:[1,0,3,2] row_mask:0xf bank_mask:0xf
	v_cndmask_b32_e32 v73, v201, v73, vcc
	v_cndmask_b32_e32 v69, v69, v201, vcc
	v_mov_b32_dpp v200, v78 quad_perm:[1,0,3,2] row_mask:0xf bank_mask:0xf
	v_cndmask_b32_dpp v201, v74, v200, vcc quad_perm:[1,0,3,2] row_mask:0xf bank_mask:0xf
	v_cndmask_b32_e32 v78, v201, v78, vcc
	v_cndmask_b32_e32 v74, v74, v201, vcc
	v_mov_b32_dpp v200, v79 quad_perm:[1,0,3,2] row_mask:0xf bank_mask:0xf
	v_cndmask_b32_dpp v201, v75, v200, vcc quad_perm:[1,0,3,2] row_mask:0xf bank_mask:0xf
	v_cndmask_b32_e32 v79, v201, v79, vcc
	v_cndmask_b32_e32 v75, v75, v201, vcc
	v_mov_b32_dpp v200, v80 quad_perm:[1,0,3,2] row_mask:0xf bank_mask:0xf
	v_cndmask_b32_dpp v201, v76, v200, vcc quad_perm:[1,0,3,2] row_mask:0xf bank_mask:0xf
	v_cndmask_b32_e32 v80, v201, v80, vcc
	v_cndmask_b32_e32 v76, v76, v201, vcc
	v_mov_b32_dpp v200, v81 quad_perm:[1,0,3,2] row_mask:0xf bank_mask:0xf
	v_cndmask_b32_dpp v201, v77, v200, vcc quad_perm:[1,0,3,2] row_mask:0xf bank_mask:0xf
	v_cndmask_b32_e32 v81, v201, v81, vcc
	v_cndmask_b32_e32 v77, v77, v201, vcc
	s_waitcnt vmcnt(24)
;     ...
; #pragma unroll
;     for (int ai = 0; ai < 2; ++ai)
; #pragma unroll
;       for (int m = 0; m < 4; ++m)
;         epi(brow + ai * HALF + wr * 64 + m * 16 + fr, bcol + wc * 32, fq, acc[ai][0][m][0], acc[ai][0][m][1], acc[ai][1][m][0], acc[ai][1][m][1]);
	v_pk_add_f32 v[236:237], v[70:71], v[236:237]
	v_pk_add_f32 v[238:239], v[72:73], v[238:239]
	v_pk_add_f32 v[240:241], v[66:67], v[240:241]
	v_pk_add_f32 v[242:243], v[68:69], v[242:243]
	v_pk_add_f32 v[244:245], v[78:79], v[244:245]
	v_pk_add_f32 v[246:247], v[80:81], v[246:247]
	v_pk_add_f32 v[248:249], v[74:75], v[248:249]
	v_pk_add_f32 v[250:251], v[76:77], v[250:251]
	global_store_dwordx4 v[150:151], v[236:239], off
	global_store_dwordx4 v[152:153], v[240:243], off
	global_store_dwordx4 v[150:151], v[244:247], off offset:512
	global_store_dwordx4 v[152:153], v[248:251], off offset:512
	s_nop 1
	s_mov_b64 s[6:7], 0xb0000
	v_lshl_add_u64 v[150:151], v[132:133], 0, s[6:7]
	v_lshl_add_u64 v[152:153], v[136:137], 0, s[6:7]
	global_load_dwordx4 v[236:239], v[150:151], off
	global_load_dwordx4 v[240:243], v[152:153], off
	global_load_dwordx4 v[244:247], v[150:151], off offset:512
	global_load_dwordx4 v[248:251], v[152:153], off offset:512
	v_mov_b32_dpp v200, v54 quad_perm:[1,0,3,2] row_mask:0xf bank_mask:0xf
	v_cndmask_b32_dpp v201, v50, v200, vcc quad_perm:[1,0,3,2] row_mask:0xf bank_mask:0xf
	v_cndmask_b32_e32 v54, v201, v54, vcc
	v_cndmask_b32_e32 v50, v50, v201, vcc
	v_mov_b32_dpp v200, v55 quad_perm:[1,0,3,2] row_mask:0xf bank_mask:0xf
	v_cndmask_b32_dpp v201, v51, v200, vcc quad_perm:[1,0,3,2] row_mask:0xf bank_mask:0xf
	v_cndmask_b32_e32 v55, v201, v55, vcc
	v_cndmask_b32_e32 v51, v51, v201, vcc
	v_mov_b32_dpp v200, v56 quad_perm:[1,0,3,2] row_mask:0xf bank_mask:0xf
	v_cndmask_b32_dpp v201, v52, v200, vcc quad_perm:[1,0,3,2] row_mask:0xf bank_mask:0xf
	v_cndmask_b32_e32 v56, v201, v56, vcc
	v_cndmask_b32_e32 v52, v52, v201, vcc
	v_mov_b32_dpp v200, v57 quad_perm:[1,0,3,2] row_mask:0xf bank_mask:0xf
	v_cndmask_b32_dpp v201, v53, v200, vcc quad_perm:[1,0,3,2] row_mask:0xf bank_mask:0xf
	v_cndmask_b32_e32 v57, v201, v57, vcc
	v_cndmask_b32_e32 v53, v53, v201, vcc
	v_mov_b32_dpp v200, v62 quad_perm:[1,0,3,2] row_mask:0xf bank_mask:0xf
	v_cndmask_b32_dpp v201, v58, v200, vcc quad_perm:[1,0,3,2] row_mask:0xf bank_mask:0xf
	v_cndmask_b32_e32 v62, v201, v62, vcc
	v_cndmask_b32_e32 v58, v58, v201, vcc
	v_mov_b32_dpp v200, v63 quad_perm:[1,0,3,2] row_mask:0xf bank_mask:0xf
	v_cndmask_b32_dpp v201, v59, v200, vcc quad_perm:[1,0,3,2] row_mask:0xf bank_mask:0xf
	v_cndmask_b32_e32 v63, v201, v63, vcc
	v_cndmask_b32_e32 v59, v59, v201, vcc
	v_mov_b32_dpp v200, v64 quad_perm:[1,0,3,2] row_mask:0xf bank_mask:0xf
	v_cndmask_b32_dpp v201, v60, v200, vcc quad_perm:[1,0,3,2] row_mask:0xf bank_mask:0xf
	v_cndmask_b32_e32 v64, v201, v64, vcc
	v_cndmask_b32_e32 v60, v60, v201, vcc
	v_mov_b32_dpp v200, v65 quad_perm:[1,0,3,2] row_mask:0xf bank_mask:0xf
	v_cndmask_b32_dpp v201, v61, v200, vcc quad_perm:[1,0,3,2] row_mask:0xf bank_mask:0xf
	v_cndmask_b32_e32 v65, v201, v65, vcc
	v_cndmask_b32_e32 v61, v61, v201, vcc
	s_waitcnt vmcnt(24)
	v_pk_add_f32 v[168:169], v[54:55], v[168:169]
	v_pk_add_f32 v[170:171], v[56:57], v[170:171]
	v_pk_add_f32 v[172:173], v[50:51], v[172:173]
	v_pk_add_f32 v[174:175], v[52:53], v[174:175]
	v_pk_add_f32 v[176:177], v[62:63], v[176:177]
	v_pk_add_f32 v[178:179], v[64:65], v[178:179]
	v_pk_add_f32 v[180:181], v[58:59], v[180:181]
	v_pk_add_f32 v[182:183], v[60:61], v[182:183]
	global_store_dwordx4 v[138:139], v[168:171], off
	global_store_dwordx4 v[140:141], v[172:175], off
	global_store_dwordx4 v[138:139], v[176:179], off offset:512
	global_store_dwordx4 v[140:141], v[180:183], off offset:512
	v_mov_b32_dpp v200, v38 quad_perm:[1,0,3,2] row_mask:0xf bank_mask:0xf
	v_cndmask_b32_dpp v201, v34, v200, vcc quad_perm:[1,0,3,2] row_mask:0xf bank_mask:0xf
	v_cndmask_b32_e32 v38, v201, v38, vcc
	v_cndmask_b32_e32 v34, v34, v201, vcc
	v_mov_b32_dpp v200, v39 quad_perm:[1,0,3,2] row_mask:0xf bank_mask:0xf
	v_cndmask_b32_dpp v201, v35, v200, vcc quad_perm:[1,0,3,2] row_mask:0xf bank_mask:0xf
	v_cndmask_b32_e32 v39, v201, v39, vcc
	v_cndmask_b32_e32 v35, v35, v201, vcc
	v_mov_b32_dpp v200, v40 quad_perm:[1,0,3,2] row_mask:0xf bank_mask:0xf
	v_cndmask_b32_dpp v201, v36, v200, vcc quad_perm:[1,0,3,2] row_mask:0xf bank_mask:0xf
	v_cndmask_b32_e32 v40, v201, v40, vcc
	v_cndmask_b32_e32 v36, v36, v201, vcc
	v_mov_b32_dpp v200, v41 quad_perm:[1,0,3,2] row_mask:0xf bank_mask:0xf
	v_cndmask_b32_dpp v201, v37, v200, vcc quad_perm:[1,0,3,2] row_mask:0xf bank_mask:0xf
	v_cndmask_b32_e32 v41, v201, v41, vcc
	v_cndmask_b32_e32 v37, v37, v201, vcc
	v_mov_b32_dpp v200, v46 quad_perm:[1,0,3,2] row_mask:0xf bank_mask:0xf
	v_cndmask_b32_dpp v201, v42, v200, vcc quad_perm:[1,0,3,2] row_mask:0xf bank_mask:0xf
	v_cndmask_b32_e32 v46, v201, v46, vcc
	v_cndmask_b32_e32 v42, v42, v201, vcc
	v_mov_b32_dpp v200, v47 quad_perm:[1,0,3,2] row_mask:0xf bank_mask:0xf
	v_cndmask_b32_dpp v201, v43, v200, vcc quad_perm:[1,0,3,2] row_mask:0xf bank_mask:0xf
	v_cndmask_b32_e32 v47, v201, v47, vcc
	v_cndmask_b32_e32 v43, v43, v201, vcc
	v_mov_b32_dpp v200, v48 quad_perm:[1,0,3,2] row_mask:0xf bank_mask:0xf
	v_cndmask_b32_dpp v201, v44, v200, vcc quad_perm:[1,0,3,2] row_mask:0xf bank_mask:0xf
	v_cndmask_b32_e32 v48, v201, v48, vcc
	v_cndmask_b32_e32 v44, v44, v201, vcc
	v_mov_b32_dpp v200, v49 quad_perm:[1,0,3,2] row_mask:0xf bank_mask:0xf
	v_cndmask_b32_dpp v201, v45, v200, vcc quad_perm:[1,0,3,2] row_mask:0xf bank_mask:0xf
	v_cndmask_b32_e32 v49, v201, v49, vcc
	v_cndmask_b32_e32 v45, v45, v201, vcc
	s_waitcnt vmcnt(20)
; #define WAIT_V(n) asm volatile("s_waitcnt vmcnt(" #n ")" ::: "memory")
;     ...
; #pragma unroll
;     for (int ai = 0; ai < 2; ++ai)
; #pragma unroll
;       for (int m = 0; m < 4; ++m)
;         epi(brow + ai * HALF + wr * 64 + m * 16 + fr, bcol + wc * 32, fq, acc[ai][0][m][0], acc[ai][0][m][1], acc[ai][1][m][0], acc[ai][1][m][1]);
;     ...
;   if (!have_next) { WAIT_V(0); __syncthreads(); }
	v_pk_add_f32 v[184:185], v[38:39], v[184:185]
	v_pk_add_f32 v[186:187], v[40:41], v[186:187]
	v_pk_add_f32 v[188:189], v[34:35], v[188:189]
	v_pk_add_f32 v[190:191], v[36:37], v[190:191]
	v_pk_add_f32 v[192:193], v[46:47], v[192:193]
	v_pk_add_f32 v[194:195], v[48:49], v[194:195]
	v_pk_add_f32 v[196:197], v[42:43], v[196:197]
	v_pk_add_f32 v[198:199], v[44:45], v[198:199]
	global_store_dwordx4 v[142:143], v[184:187], off
	global_store_dwordx4 v[144:145], v[188:191], off
	global_store_dwordx4 v[142:143], v[192:195], off offset:512
	global_store_dwordx4 v[144:145], v[196:199], off offset:512
	v_mov_b32_dpp v200, v22 quad_perm:[1,0,3,2] row_mask:0xf bank_mask:0xf
	v_cndmask_b32_dpp v201, v18, v200, vcc quad_perm:[1,0,3,2] row_mask:0xf bank_mask:0xf
	v_cndmask_b32_e32 v22, v201, v22, vcc
	v_cndmask_b32_e32 v18, v18, v201, vcc
	v_mov_b32_dpp v200, v23 quad_perm:[1,0,3,2] row_mask:0xf bank_mask:0xf
	v_cndmask_b32_dpp v201, v19, v200, vcc quad_perm:[1,0,3,2] row_mask:0xf bank_mask:0xf
	v_cndmask_b32_e32 v23, v201, v23, vcc
	v_cndmask_b32_e32 v19, v19, v201, vcc
	v_mov_b32_dpp v200, v24 quad_perm:[1,0,3,2] row_mask:0xf bank_mask:0xf
	v_cndmask_b32_dpp v201, v20, v200, vcc quad_perm:[1,0,3,2] row_mask:0xf bank_mask:0xf
	v_cndmask_b32_e32 v24, v201, v24, vcc
	v_cndmask_b32_e32 v20, v20, v201, vcc
	v_mov_b32_dpp v200, v25 quad_perm:[1,0,3,2] row_mask:0xf bank_mask:0xf
	v_cndmask_b32_dpp v201, v21, v200, vcc quad_perm:[1,0,3,2] row_mask:0xf bank_mask:0xf
	v_cndmask_b32_e32 v25, v201, v25, vcc
	v_cndmask_b32_e32 v21, v21, v201, vcc
	v_mov_b32_dpp v200, v30 quad_perm:[1,0,3,2] row_mask:0xf bank_mask:0xf
	v_cndmask_b32_dpp v201, v26, v200, vcc quad_perm:[1,0,3,2] row_mask:0xf bank_mask:0xf
	v_cndmask_b32_e32 v30, v201, v30, vcc
	v_cndmask_b32_e32 v26, v26, v201, vcc
	v_mov_b32_dpp v200, v31 quad_perm:[1,0,3,2] row_mask:0xf bank_mask:0xf
	v_cndmask_b32_dpp v201, v27, v200, vcc quad_perm:[1,0,3,2] row_mask:0xf bank_mask:0xf
	v_cndmask_b32_e32 v31, v201, v31, vcc
	v_cndmask_b32_e32 v27, v27, v201, vcc
	v_mov_b32_dpp v200, v32 quad_perm:[1,0,3,2] row_mask:0xf bank_mask:0xf
	v_cndmask_b32_dpp v201, v28, v200, vcc quad_perm:[1,0,3,2] row_mask:0xf bank_mask:0xf
	v_cndmask_b32_e32 v32, v201, v32, vcc
	v_cndmask_b32_e32 v28, v28, v201, vcc
	v_mov_b32_dpp v200, v33 quad_perm:[1,0,3,2] row_mask:0xf bank_mask:0xf
	v_cndmask_b32_dpp v201, v29, v200, vcc quad_perm:[1,0,3,2] row_mask:0xf bank_mask:0xf
	v_cndmask_b32_e32 v33, v201, v33, vcc
	v_cndmask_b32_e32 v29, v29, v201, vcc
	s_waitcnt vmcnt(16)
	v_pk_add_f32 v[220:221], v[22:23], v[220:221]
	v_pk_add_f32 v[222:223], v[24:25], v[222:223]
	v_pk_add_f32 v[224:225], v[18:19], v[224:225]
	v_pk_add_f32 v[226:227], v[20:21], v[226:227]
	v_pk_add_f32 v[228:229], v[30:31], v[228:229]
	v_pk_add_f32 v[230:231], v[32:33], v[230:231]
	v_pk_add_f32 v[232:233], v[26:27], v[232:233]
	v_pk_add_f32 v[234:235], v[28:29], v[234:235]
	global_store_dwordx4 v[146:147], v[220:223], off
	global_store_dwordx4 v[148:149], v[224:227], off
	global_store_dwordx4 v[146:147], v[228:231], off offset:512
	global_store_dwordx4 v[148:149], v[232:235], off offset:512
	v_mov_b32_dpp v200, v14 quad_perm:[1,0,3,2] row_mask:0xf bank_mask:0xf
	v_cndmask_b32_dpp v201, v6, v200, vcc quad_perm:[1,0,3,2] row_mask:0xf bank_mask:0xf
	v_cndmask_b32_e32 v14, v201, v14, vcc
	v_cndmask_b32_e32 v6, v6, v201, vcc
	v_mov_b32_dpp v200, v15 quad_perm:[1,0,3,2] row_mask:0xf bank_mask:0xf
	v_cndmask_b32_dpp v201, v7, v200, vcc quad_perm:[1,0,3,2] row_mask:0xf bank_mask:0xf
	v_cndmask_b32_e32 v15, v201, v15, vcc
	v_cndmask_b32_e32 v7, v7, v201, vcc
	v_mov_b32_dpp v200, v16 quad_perm:[1,0,3,2] row_mask:0xf bank_mask:0xf
	v_cndmask_b32_dpp v201, v8, v200, vcc quad_perm:[1,0,3,2] row_mask:0xf bank_mask:0xf
	v_cndmask_b32_e32 v16, v201, v16, vcc
	v_cndmask_b32_e32 v8, v8, v201, vcc
	v_mov_b32_dpp v200, v17 quad_perm:[1,0,3,2] row_mask:0xf bank_mask:0xf
	v_cndmask_b32_dpp v201, v9, v200, vcc quad_perm:[1,0,3,2] row_mask:0xf bank_mask:0xf
	v_cndmask_b32_e32 v17, v201, v17, vcc
	v_cndmask_b32_e32 v9, v9, v201, vcc
	v_mov_b32_dpp v200, v10 quad_perm:[1,0,3,2] row_mask:0xf bank_mask:0xf
	v_cndmask_b32_dpp v201, v2, v200, vcc quad_perm:[1,0,3,2] row_mask:0xf bank_mask:0xf
	v_cndmask_b32_e32 v10, v201, v10, vcc
	v_cndmask_b32_e32 v2, v2, v201, vcc
	v_mov_b32_dpp v200, v11 quad_perm:[1,0,3,2] row_mask:0xf bank_mask:0xf
	v_cndmask_b32_dpp v201, v3, v200, vcc quad_perm:[1,0,3,2] row_mask:0xf bank_mask:0xf
	v_cndmask_b32_e32 v11, v201, v11, vcc
	v_cndmask_b32_e32 v3, v3, v201, vcc
	v_mov_b32_dpp v200, v12 quad_perm:[1,0,3,2] row_mask:0xf bank_mask:0xf
	v_cndmask_b32_dpp v201, v4, v200, vcc quad_perm:[1,0,3,2] row_mask:0xf bank_mask:0xf
	v_cndmask_b32_e32 v12, v201, v12, vcc
	v_cndmask_b32_e32 v4, v4, v201, vcc
	v_mov_b32_dpp v200, v13 quad_perm:[1,0,3,2] row_mask:0xf bank_mask:0xf
	v_cndmask_b32_dpp v201, v5, v200, vcc quad_perm:[1,0,3,2] row_mask:0xf bank_mask:0xf
	v_cndmask_b32_e32 v13, v201, v13, vcc
	v_cndmask_b32_e32 v5, v5, v201, vcc
	s_waitcnt vmcnt(12)
	v_pk_add_f32 v[236:237], v[14:15], v[236:237]
	v_pk_add_f32 v[238:239], v[16:17], v[238:239]
	v_pk_add_f32 v[240:241], v[6:7], v[240:241]
	v_pk_add_f32 v[242:243], v[8:9], v[242:243]
	v_pk_add_f32 v[244:245], v[10:11], v[244:245]
	v_pk_add_f32 v[246:247], v[12:13], v[246:247]
	v_pk_add_f32 v[248:249], v[2:3], v[248:249]
	v_pk_add_f32 v[250:251], v[4:5], v[250:251]
	global_store_dwordx4 v[150:151], v[236:239], off
	global_store_dwordx4 v[152:153], v[240:243], off
	global_store_dwordx4 v[150:151], v[244:247], off offset:512
	global_store_dwordx4 v[152:153], v[248:251], off offset:512
	v_cmp_ne_u32_e64 s[6:7], 1, v0
	s_andn2_b64 vcc, exec, s[4:5]
	s_cbranch_vccnz .LBB0_1450
	s_waitcnt vmcnt(0)
	s_waitcnt lgkmcnt(0)
	s_barrier
	s_branch .LBB0_1450

;     ...
; #pragma unroll
;     for (int ai = 0; ai < 2; ++ai)
; #pragma unroll
;       for (int m = 0; m < 4; ++m)
;         epi(brow + ai * HALF + wr * 64 + m * 16 + fr, bcol + wc * 32, fq, acc[ai][0][m][0], acc[ai][0][m][1], acc[ai][1][m][0], acc[ai][1][m][1]);
.LBB0_1564:
	v_or_b32_e32 v0, s16, v140
	v_add_u32_e32 v136, v0, v141
	v_ashrrev_i32_e32 v137, 31, v136
	v_readlane_b32 s4, v253, 60
	v_lshl_or_b32 v0, v139, 5, s15
	v_lshlrev_b64 v[132:133], 12, v[136:137]
	v_readlane_b32 s5, v253, 61
	v_lshlrev_b64 v[134:135], 2, v[0:1]
	v_mov_b32_e32 v131, v1
	v_lshl_add_u64 v[132:133], s[4:5], 0, v[132:133]
	v_lshl_add_u64 v[132:133], v[132:133], 0, v[134:135]
	v_lshl_add_u64 v[132:133], v[132:133], 0, v[130:131]
	v_cndmask_b32_e64 v0, 0, 1, s[2:3]
	v_and_b32_e32 v134, 1, v210
	v_cmp_eq_u32_e32 vcc, 0, v134
	s_nop 1
	v_mov_b32_e32 v135, 0xfffff040
	v_cndmask_b32_e32 v134, v135, v1, vcc
	v_cndmask_b32_e32 v135, -1, v1, vcc
	v_lshl_add_u64 v[132:133], v[132:133], 0, v[134:135]
	s_mov_b64 s[4:5], 0x1000
	v_lshl_add_u64 v[136:137], v[132:133], 0, s[4:5]
	v_mov_b64_e32 v[138:139], v[132:133]
	v_mov_b64_e32 v[140:141], v[136:137]
	global_load_dwordx4 v[168:171], v[138:139], off
	global_load_dwordx4 v[172:175], v[140:141], off
	global_load_dwordx4 v[176:179], v[138:139], off offset:512
	global_load_dwordx4 v[180:183], v[140:141], off offset:512
	s_mov_b64 s[4:5], 0x10000
	v_lshl_add_u64 v[142:143], v[132:133], 0, s[4:5]
	v_lshl_add_u64 v[144:145], v[136:137], 0, s[4:5]
	global_load_dwordx4 v[184:187], v[142:143], off
	global_load_dwordx4 v[188:191], v[144:145], off
	global_load_dwordx4 v[192:195], v[142:143], off offset:512
	global_load_dwordx4 v[196:199], v[144:145], off offset:512
	s_mov_b64 s[4:5], 0x20000
	v_lshl_add_u64 v[146:147], v[132:133], 0, s[4:5]
	v_lshl_add_u64 v[148:149], v[136:137], 0, s[4:5]
	global_load_dwordx4 v[220:223], v[146:147], off
	global_load_dwordx4 v[224:227], v[148:149], off
	global_load_dwordx4 v[228:231], v[146:147], off offset:512
	global_load_dwordx4 v[232:235], v[148:149], off offset:512
	s_mov_b64 s[4:5], 0x30000
	v_lshl_add_u64 v[150:151], v[132:133], 0, s[4:5]
	v_lshl_add_u64 v[152:153], v[136:137], 0, s[4:5]
	global_load_dwordx4 v[236:239], v[150:151], off
	global_load_dwordx4 v[240:243], v[152:153], off
	global_load_dwordx4 v[244:247], v[150:151], off offset:512
	global_load_dwordx4 v[248:251], v[152:153], off offset:512
	v_mov_b32_dpp v200, v118 quad_perm:[1,0,3,2] row_mask:0xf bank_mask:0xf
	v_cndmask_b32_dpp v201, v114, v200, vcc quad_perm:[1,0,3,2] row_mask:0xf bank_mask:0xf
	v_cndmask_b32_e32 v118, v201, v118, vcc
	v_cndmask_b32_e32 v114, v114, v201, vcc
	v_mov_b32_dpp v200, v119 quad_perm:[1,0,3,2] row_mask:0xf bank_mask:0xf
	v_cndmask_b32_dpp v201, v115, v200, vcc quad_perm:[1,0,3,2] row_mask:0xf bank_mask:0xf
	v_cndmask_b32_e32 v119, v201, v119, vcc
	v_cndmask_b32_e32 v115, v115, v201, vcc
	v_mov_b32_dpp v200, v120 quad_perm:[1,0,3,2] row_mask:0xf bank_mask:0xf
	v_cndmask_b32_dpp v201, v116, v200, vcc quad_perm:[1,0,3,2] row_mask:0xf bank_mask:0xf
	v_cndmask_b32_e32 v120, v201, v120, vcc
	v_cndmask_b32_e32 v116, v116, v201, vcc
	v_mov_b32_dpp v200, v121 quad_perm:[1,0,3,2] row_mask:0xf bank_mask:0xf
	v_cndmask_b32_dpp v201, v117, v200, vcc quad_perm:[1,0,3,2] row_mask:0xf bank_mask:0xf
	v_cndmask_b32_e32 v121, v201, v121, vcc
	v_cndmask_b32_e32 v117, v117, v201, vcc
	v_mov_b32_dpp v200, v126 quad_perm:[1,0,3,2] row_mask:0xf bank_mask:0xf
	v_cndmask_b32_dpp v201, v122, v200, vcc quad_perm:[1,0,3,2] row_mask:0xf bank_mask:0xf
	v_cndmask_b32_e32 v126, v201, v126, vcc
	v_cndmask_b32_e32 v122, v122, v201, vcc
	v_mov_b32_dpp v200, v127 quad_perm:[1,0,3,2] row_mask:0xf bank_mask:0xf
	v_cndmask_b32_dpp v201, v123, v200, vcc quad_perm:[1,0,3,2] row_mask:0xf bank_mask:0xf
	v_cndmask_b32_e32 v127, v201, v127, vcc
	v_cndmask_b32_e32 v123, v123, v201, vcc
	v_mov_b32_dpp v200, v128 quad_perm:[1,0,3,2] row_mask:0xf bank_mask:0xf
	v_cndmask_b32_dpp v201, v124, v200, vcc quad_perm:[1,0,3,2] row_mask:0xf bank_mask:0xf
	v_cndmask_b32_e32 v128, v201, v128, vcc
	v_cndmask_b32_e32 v124, v124, v201, vcc
	v_mov_b32_dpp v200, v129 quad_perm:[1,0,3,2] row_mask:0xf bank_mask:0xf
	v_cndmask_b32_dpp v201, v125, v200, vcc quad_perm:[1,0,3,2] row_mask:0xf bank_mask:0xf
	v_cndmask_b32_e32 v129, v201, v129, vcc
	v_cndmask_b32_e32 v125, v125, v201, vcc
	s_waitcnt vmcnt(12)
	v_pk_add_f32 v[168:169], v[118:119], v[168:169]
	v_pk_add_f32 v[170:171], v[120:121], v[170:171]
	v_pk_add_f32 v[172:173], v[114:115], v[172:173]
	v_pk_add_f32 v[174:175], v[116:117], v[174:175]
	v_pk_add_f32 v[176:177], v[126:127], v[176:177]
	v_pk_add_f32 v[178:179], v[128:129], v[178:179]
	v_pk_add_f32 v[180:181], v[122:123], v[180:181]
	v_pk_add_f32 v[182:183], v[124:125], v[182:183]
	global_store_dwordx4 v[138:139], v[168:171], off
	global_store_dwordx4 v[140:141], v[172:175], off
	global_store_dwordx4 v[138:139], v[176:179], off offset:512
	global_store_dwordx4 v[140:141], v[180:183], off offset:512
	s_nop 1
	s_mov_b64 s[4:5], 0x80000
	v_lshl_add_u64 v[138:139], v[132:133], 0, s[4:5]
	v_lshl_add_u64 v[140:141], v[136:137], 0, s[4:5]
	global_load_dwordx4 v[168:171], v[138:139], off
	global_load_dwordx4 v[172:175], v[140:141], off
	global_load_dwordx4 v[176:179], v[138:139], off offset:512
	global_load_dwordx4 v[180:183], v[140:141], off offset:512
	v_mov_b32_dpp v200, v102 quad_perm:[1,0,3,2] row_mask:0xf bank_mask:0xf
	v_cndmask_b32_dpp v201, v98, v200, vcc quad_perm:[1,0,3,2] row_mask:0xf bank_mask:0xf
	v_cndmask_b32_e32 v102, v201, v102, vcc
	v_cndmask_b32_e32 v98, v98, v201, vcc
	v_mov_b32_dpp v200, v103 quad_perm:[1,0,3,2] row_mask:0xf bank_mask:0xf
	v_cndmask_b32_dpp v201, v99, v200, vcc quad_perm:[1,0,3,2] row_mask:0xf bank_mask:0xf
	v_cndmask_b32_e32 v103, v201, v103, vcc
	v_cndmask_b32_e32 v99, v99, v201, vcc
	v_mov_b32_dpp v200, v104 quad_perm:[1,0,3,2] row_mask:0xf bank_mask:0xf
	v_cndmask_b32_dpp v201, v100, v200, vcc quad_perm:[1,0,3,2] row_mask:0xf bank_mask:0xf
	v_cndmask_b32_e32 v104, v201, v104, vcc
	v_cndmask_b32_e32 v100, v100, v201, vcc
	v_mov_b32_dpp v200, v105 quad_perm:[1,0,3,2] row_mask:0xf bank_mask:0xf
	v_cndmask_b32_dpp v201, v101, v200, vcc quad_perm:[1,0,3,2] row_mask:0xf bank_mask:0xf
	v_cndmask_b32_e32 v105, v201, v105, vcc
	v_cndmask_b32_e32 v101, v101, v201, vcc
	v_mov_b32_dpp v200, v110 quad_perm:[1,0,3,2] row_mask:0xf bank_mask:0xf
	v_cndmask_b32_dpp v201, v106, v200, vcc quad_perm:[1,0,3,2] row_mask:0xf bank_mask:0xf
	v_cndmask_b32_e32 v110, v201, v110, vcc
	v_cndmask_b32_e32 v106, v106, v201, vcc
	v_mov_b32_dpp v200, v111 quad_perm:[1,0,3,2] row_mask:0xf bank_mask:0xf
	v_cndmask_b32_dpp v201, v107, v200, vcc quad_perm:[1,0,3,2] row_mask:0xf bank_mask:0xf
	v_cndmask_b32_e32 v111, v201, v111, vcc
	v_cndmask_b32_e32 v107, v107, v201, vcc
	v_mov_b32_dpp v200, v112 quad_perm:[1,0,3,2] row_mask:0xf bank_mask:0xf
	v_cndmask_b32_dpp v201, v108, v200, vcc quad_perm:[1,0,3,2] row_mask:0xf bank_mask:0xf
	v_cndmask_b32_e32 v112, v201, v112, vcc
	v_cndmask_b32_e32 v108, v108, v201, vcc
	v_mov_b32_dpp v200, v113 quad_perm:[1,0,3,2] row_mask:0xf bank_mask:0xf
	v_cndmask_b32_dpp v201, v109, v200, vcc quad_perm:[1,0,3,2] row_mask:0xf bank_mask:0xf
	v_cndmask_b32_e32 v113, v201, v113, vcc
	v_cndmask_b32_e32 v109, v109, v201, vcc
	s_waitcnt vmcnt(16)
;     ...
; #pragma unroll
;     for (int ai = 0; ai < 2; ++ai)
; #pragma unroll
;       for (int m = 0; m < 4; ++m)
;         epi(brow + ai * HALF + wr * 64 + m * 16 + fr, bcol + wc * 32, fq, acc[ai][0][m][0], acc[ai][0][m][1], acc[ai][1][m][0], acc[ai][1][m][1]);
	v_pk_add_f32 v[184:185], v[102:103], v[184:185]
	v_pk_add_f32 v[186:187], v[104:105], v[186:187]
	v_pk_add_f32 v[188:189], v[98:99], v[188:189]
	v_pk_add_f32 v[190:191], v[100:101], v[190:191]
	v_pk_add_f32 v[192:193], v[110:111], v[192:193]
	v_pk_add_f32 v[194:195], v[112:113], v[194:195]
	v_pk_add_f32 v[196:197], v[106:107], v[196:197]
	v_pk_add_f32 v[198:199], v[108:109], v[198:199]
	global_store_dwordx4 v[142:143], v[184:187], off
	global_store_dwordx4 v[144:145], v[188:191], off
	global_store_dwordx4 v[142:143], v[192:195], off offset:512
	global_store_dwordx4 v[144:145], v[196:199], off offset:512
	s_nop 1
	s_mov_b64 s[4:5], 0x90000
	v_lshl_add_u64 v[142:143], v[132:133], 0, s[4:5]
	v_lshl_add_u64 v[144:145], v[136:137], 0, s[4:5]
	global_load_dwordx4 v[184:187], v[142:143], off
	global_load_dwordx4 v[188:191], v[144:145], off
	global_load_dwordx4 v[192:195], v[142:143], off offset:512
	global_load_dwordx4 v[196:199], v[144:145], off offset:512
	v_mov_b32_dpp v200, v86 quad_perm:[1,0,3,2] row_mask:0xf bank_mask:0xf
	v_cndmask_b32_dpp v201, v82, v200, vcc quad_perm:[1,0,3,2] row_mask:0xf bank_mask:0xf
	v_cndmask_b32_e32 v86, v201, v86, vcc
	v_cndmask_b32_e32 v82, v82, v201, vcc
	v_mov_b32_dpp v200, v87 quad_perm:[1,0,3,2] row_mask:0xf bank_mask:0xf
	v_cndmask_b32_dpp v201, v83, v200, vcc quad_perm:[1,0,3,2] row_mask:0xf bank_mask:0xf
	v_cndmask_b32_e32 v87, v201, v87, vcc
	v_cndmask_b32_e32 v83, v83, v201, vcc
	v_mov_b32_dpp v200, v88 quad_perm:[1,0,3,2] row_mask:0xf bank_mask:0xf
	v_cndmask_b32_dpp v201, v84, v200, vcc quad_perm:[1,0,3,2] row_mask:0xf bank_mask:0xf
	v_cndmask_b32_e32 v88, v201, v88, vcc
	v_cndmask_b32_e32 v84, v84, v201, vcc
	v_mov_b32_dpp v200, v89 quad_perm:[1,0,3,2] row_mask:0xf bank_mask:0xf
	v_cndmask_b32_dpp v201, v85, v200, vcc quad_perm:[1,0,3,2] row_mask:0xf bank_mask:0xf
	v_cndmask_b32_e32 v89, v201, v89, vcc
	v_cndmask_b32_e32 v85, v85, v201, vcc
	v_mov_b32_dpp v200, v94 quad_perm:[1,0,3,2] row_mask:0xf bank_mask:0xf
	v_cndmask_b32_dpp v201, v90, v200, vcc quad_perm:[1,0,3,2] row_mask:0xf bank_mask:0xf
	v_cndmask_b32_e32 v94, v201, v94, vcc
	v_cndmask_b32_e32 v90, v90, v201, vcc
	v_mov_b32_dpp v200, v95 quad_perm:[1,0,3,2] row_mask:0xf bank_mask:0xf
	v_cndmask_b32_dpp v201, v91, v200, vcc quad_perm:[1,0,3,2] row_mask:0xf bank_mask:0xf
	v_cndmask_b32_e32 v95, v201, v95, vcc
	v_cndmask_b32_e32 v91, v91, v201, vcc
	v_mov_b32_dpp v200, v96 quad_perm:[1,0,3,2] row_mask:0xf bank_mask:0xf
	v_cndmask_b32_dpp v201, v92, v200, vcc quad_perm:[1,0,3,2] row_mask:0xf bank_mask:0xf
	v_cndmask_b32_e32 v96, v201, v96, vcc
	v_cndmask_b32_e32 v92, v92, v201, vcc
	v_mov_b32_dpp v200, v97 quad_perm:[1,0,3,2] row_mask:0xf bank_mask:0xf
	v_cndmask_b32_dpp v201, v93, v200, vcc quad_perm:[1,0,3,2] row_mask:0xf bank_mask:0xf
	v_cndmask_b32_e32 v97, v201, v97, vcc
	v_cndmask_b32_e32 v93, v93, v201, vcc
	s_waitcnt vmcnt(20)
	v_pk_add_f32 v[220:221], v[86:87], v[220:221]
	v_pk_add_f32 v[222:223], v[88:89], v[222:223]
	v_pk_add_f32 v[224:225], v[82:83], v[224:225]
	v_pk_add_f32 v[226:227], v[84:85], v[226:227]
	v_pk_add_f32 v[228:229], v[94:95], v[228:229]
	v_pk_add_f32 v[230:231], v[96:97], v[230:231]
	v_pk_add_f32 v[232:233], v[90:91], v[232:233]
	v_pk_add_f32 v[234:235], v[92:93], v[234:235]
	global_store_dwordx4 v[146:147], v[220:223], off
	global_store_dwordx4 v[148:149], v[224:227], off
	global_store_dwordx4 v[146:147], v[228:231], off offset:512
	global_store_dwordx4 v[148:149], v[232:235], off offset:512
	s_nop 1
	s_mov_b64 s[4:5], 0xa0000
	v_lshl_add_u64 v[146:147], v[132:133], 0, s[4:5]
	v_lshl_add_u64 v[148:149], v[136:137], 0, s[4:5]
	global_load_dwordx4 v[220:223], v[146:147], off
	global_load_dwordx4 v[224:227], v[148:149], off
	global_load_dwordx4 v[228:231], v[146:147], off offset:512
	global_load_dwordx4 v[232:235], v[148:149], off offset:512
	v_mov_b32_dpp v200, v70 quad_perm:[1,0,3,2] row_mask:0xf bank_mask:0xf
	v_cndmask_b32_dpp v201, v66, v200, vcc quad_perm:[1,0,3,2] row_mask:0xf bank_mask:0xf
	v_cndmask_b32_e32 v70, v201, v70, vcc
	v_cndmask_b32_e32 v66, v66, v201, vcc
	v_mov_b32_dpp v200, v71 quad_perm:[1,0,3,2] row_mask:0xf bank_mask:0xf
	v_cndmask_b32_dpp v201, v67, v200, vcc quad_perm:[1,0,3,2] row_mask:0xf bank_mask:0xf
	v_cndmask_b32_e32 v71, v201, v71, vcc
	v_cndmask_b32_e32 v67, v67, v201, vcc
	v_mov_b32_dpp v200, v72 quad_perm:[1,0,3,2] row_mask:0xf bank_mask:0xf
	v_cndmask_b32_dpp v201, v68, v200, vcc quad_perm:[1,0,3,2] row_mask:0xf bank_mask:0xf
	v_cndmask_b32_e32 v72, v201, v72, vcc
	v_cndmask_b32_e32 v68, v68, v201, vcc
	v_mov_b32_dpp v200, v73 quad_perm:[1,0,3,2] row_mask:0xf bank_mask:0xf
	v_cndmask_b32_dpp v201, v69, v200, vcc quad_perm:[1,0,3,2] row_mask:0xf bank_mask:0xf
	v_cndmask_b32_e32 v73, v201, v73, vcc
	v_cndmask_b32_e32 v69, v69, v201, vcc
	v_mov_b32_dpp v200, v78 quad_perm:[1,0,3,2] row_mask:0xf bank_mask:0xf
	v_cndmask_b32_dpp v201, v74, v200, vcc quad_perm:[1,0,3,2] row_mask:0xf bank_mask:0xf
	v_cndmask_b32_e32 v78, v201, v78, vcc
	v_cndmask_b32_e32 v74, v74, v201, vcc
	v_mov_b32_dpp v200, v79 quad_perm:[1,0,3,2] row_mask:0xf bank_mask:0xf
	v_cndmask_b32_dpp v201, v75, v200, vcc quad_perm:[1,0,3,2] row_mask:0xf bank_mask:0xf
	v_cndmask_b32_e32 v79, v201, v79, vcc
	v_cndmask_b32_e32 v75, v75, v201, vcc
	v_mov_b32_dpp v200, v80 quad_perm:[1,0,3,2] row_mask:0xf bank_mask:0xf
	v_cndmask_b32_dpp v201, v76, v200, vcc quad_perm:[1,0,3,2] row_mask:0xf bank_mask:0xf
	v_cndmask_b32_e32 v80, v201, v80, vcc
	v_cndmask_b32_e32 v76, v76, v201, vcc
	v_mov_b32_dpp v200, v81 quad_perm:[1,0,3,2] row_mask:0xf bank_mask:0xf
	v_cndmask_b32_dpp v201, v77, v200, vcc quad_perm:[1,0,3,2] row_mask:0xf bank_mask:0xf
	v_cndmask_b32_e32 v81, v201, v81, vcc
	v_cndmask_b32_e32 v77, v77, v201, vcc
	s_waitcnt vmcnt(24)
;     ...
; #pragma unroll
;     for (int ai = 0; ai < 2; ++ai)
; #pragma unroll
;       for (int m = 0; m < 4; ++m)
;         epi(brow + ai * HALF + wr * 64 + m * 16 + fr, bcol + wc * 32, fq, acc[ai][0][m][0], acc[ai][0][m][1], acc[ai][1][m][0], acc[ai][1][m][1]);
	v_pk_add_f32 v[236:237], v[70:71], v[236:237]
	v_pk_add_f32 v[238:239], v[72:73], v[238:239]
	v_pk_add_f32 v[240:241], v[66:67], v[240:241]
	v_pk_add_f32 v[242:243], v[68:69], v[242:243]
	v_pk_add_f32 v[244:245], v[78:79], v[244:245]
	v_pk_add_f32 v[246:247], v[80:81], v[246:247]
	v_pk_add_f32 v[248:249], v[74:75], v[248:249]
	v_pk_add_f32 v[250:251], v[76:77], v[250:251]
	global_store_dwordx4 v[150:151], v[236:239], off
	global_store_dwordx4 v[152:153], v[240:243], off
	global_store_dwordx4 v[150:151], v[244:247], off offset:512
	global_store_dwordx4 v[152:153], v[248:251], off offset:512
	s_nop 1
	s_mov_b64 s[4:5], 0xb0000
	v_lshl_add_u64 v[150:151], v[132:133], 0, s[4:5]
	v_lshl_add_u64 v[152:153], v[136:137], 0, s[4:5]
	global_load_dwordx4 v[236:239], v[150:151], off
	global_load_dwordx4 v[240:243], v[152:153], off
	global_load_dwordx4 v[244:247], v[150:151], off offset:512
	global_load_dwordx4 v[248:251], v[152:153], off offset:512
	v_mov_b32_dpp v200, v54 quad_perm:[1,0,3,2] row_mask:0xf bank_mask:0xf
	v_cndmask_b32_dpp v201, v50, v200, vcc quad_perm:[1,0,3,2] row_mask:0xf bank_mask:0xf
	v_cndmask_b32_e32 v54, v201, v54, vcc
	v_cndmask_b32_e32 v50, v50, v201, vcc
	v_mov_b32_dpp v200, v55 quad_perm:[1,0,3,2] row_mask:0xf bank_mask:0xf
	v_cndmask_b32_dpp v201, v51, v200, vcc quad_perm:[1,0,3,2] row_mask:0xf bank_mask:0xf
	v_cndmask_b32_e32 v55, v201, v55, vcc
	v_cndmask_b32_e32 v51, v51, v201, vcc
	v_mov_b32_dpp v200, v56 quad_perm:[1,0,3,2] row_mask:0xf bank_mask:0xf
	v_cndmask_b32_dpp v201, v52, v200, vcc quad_perm:[1,0,3,2] row_mask:0xf bank_mask:0xf
	v_cndmask_b32_e32 v56, v201, v56, vcc
	v_cndmask_b32_e32 v52, v52, v201, vcc
	v_mov_b32_dpp v200, v57 quad_perm:[1,0,3,2] row_mask:0xf bank_mask:0xf
	v_cndmask_b32_dpp v201, v53, v200, vcc quad_perm:[1,0,3,2] row_mask:0xf bank_mask:0xf
	v_cndmask_b32_e32 v57, v201, v57, vcc
	v_cndmask_b32_e32 v53, v53, v201, vcc
	v_mov_b32_dpp v200, v62 quad_perm:[1,0,3,2] row_mask:0xf bank_mask:0xf
	v_cndmask_b32_dpp v201, v58, v200, vcc quad_perm:[1,0,3,2] row_mask:0xf bank_mask:0xf
	v_cndmask_b32_e32 v62, v201, v62, vcc
	v_cndmask_b32_e32 v58, v58, v201, vcc
	v_mov_b32_dpp v200, v63 quad_perm:[1,0,3,2] row_mask:0xf bank_mask:0xf
	v_cndmask_b32_dpp v201, v59, v200, vcc quad_perm:[1,0,3,2] row_mask:0xf bank_mask:0xf
	v_cndmask_b32_e32 v63, v201, v63, vcc
	v_cndmask_b32_e32 v59, v59, v201, vcc
	v_mov_b32_dpp v200, v64 quad_perm:[1,0,3,2] row_mask:0xf bank_mask:0xf
	v_cndmask_b32_dpp v201, v60, v200, vcc quad_perm:[1,0,3,2] row_mask:0xf bank_mask:0xf
	v_cndmask_b32_e32 v64, v201, v64, vcc
	v_cndmask_b32_e32 v60, v60, v201, vcc
	v_mov_b32_dpp v200, v65 quad_perm:[1,0,3,2] row_mask:0xf bank_mask:0xf
	v_cndmask_b32_dpp v201, v61, v200, vcc quad_perm:[1,0,3,2] row_mask:0xf bank_mask:0xf
	v_cndmask_b32_e32 v65, v201, v65, vcc
	v_cndmask_b32_e32 v61, v61, v201, vcc
	s_waitcnt vmcnt(24)
	v_pk_add_f32 v[168:169], v[54:55], v[168:169]
	v_pk_add_f32 v[170:171], v[56:57], v[170:171]
	v_pk_add_f32 v[172:173], v[50:51], v[172:173]
	v_pk_add_f32 v[174:175], v[52:53], v[174:175]
	v_pk_add_f32 v[176:177], v[62:63], v[176:177]
	v_pk_add_f32 v[178:179], v[64:65], v[178:179]
	v_pk_add_f32 v[180:181], v[58:59], v[180:181]
	v_pk_add_f32 v[182:183], v[60:61], v[182:183]
	global_store_dwordx4 v[138:139], v[168:171], off
	global_store_dwordx4 v[140:141], v[172:175], off
	global_store_dwordx4 v[138:139], v[176:179], off offset:512
	global_store_dwordx4 v[140:141], v[180:183], off offset:512
	v_mov_b32_dpp v200, v38 quad_perm:[1,0,3,2] row_mask:0xf bank_mask:0xf
	v_cndmask_b32_dpp v201, v34, v200, vcc quad_perm:[1,0,3,2] row_mask:0xf bank_mask:0xf
	v_cndmask_b32_e32 v38, v201, v38, vcc
	v_cndmask_b32_e32 v34, v34, v201, vcc
	v_mov_b32_dpp v200, v39 quad_perm:[1,0,3,2] row_mask:0xf bank_mask:0xf
	v_cndmask_b32_dpp v201, v35, v200, vcc quad_perm:[1,0,3,2] row_mask:0xf bank_mask:0xf
	v_cndmask_b32_e32 v39, v201, v39, vcc
	v_cndmask_b32_e32 v35, v35, v201, vcc
	v_mov_b32_dpp v200, v40 quad_perm:[1,0,3,2] row_mask:0xf bank_mask:0xf
	v_cndmask_b32_dpp v201, v36, v200, vcc quad_perm:[1,0,3,2] row_mask:0xf bank_mask:0xf
	v_cndmask_b32_e32 v40, v201, v40, vcc
	v_cndmask_b32_e32 v36, v36, v201, vcc
	v_mov_b32_dpp v200, v41 quad_perm:[1,0,3,2] row_mask:0xf bank_mask:0xf
	v_cndmask_b32_dpp v201, v37, v200, vcc quad_perm:[1,0,3,2] row_mask:0xf bank_mask:0xf
	v_cndmask_b32_e32 v41, v201, v41, vcc
	v_cndmask_b32_e32 v37, v37, v201, vcc
	v_mov_b32_dpp v200, v46 quad_perm:[1,0,3,2] row_mask:0xf bank_mask:0xf
	v_cndmask_b32_dpp v201, v42, v200, vcc quad_perm:[1,0,3,2] row_mask:0xf bank_mask:0xf
	v_cndmask_b32_e32 v46, v201, v46, vcc
	v_cndmask_b32_e32 v42, v42, v201, vcc
	v_mov_b32_dpp v200, v47 quad_perm:[1,0,3,2] row_mask:0xf bank_mask:0xf
	v_cndmask_b32_dpp v201, v43, v200, vcc quad_perm:[1,0,3,2] row_mask:0xf bank_mask:0xf
	v_cndmask_b32_e32 v47, v201, v47, vcc
	v_cndmask_b32_e32 v43, v43, v201, vcc
	v_mov_b32_dpp v200, v48 quad_perm:[1,0,3,2] row_mask:0xf bank_mask:0xf
	v_cndmask_b32_dpp v201, v44, v200, vcc quad_perm:[1,0,3,2] row_mask:0xf bank_mask:0xf
	v_cndmask_b32_e32 v48, v201, v48, vcc
	v_cndmask_b32_e32 v44, v44, v201, vcc
	v_mov_b32_dpp v200, v49 quad_perm:[1,0,3,2] row_mask:0xf bank_mask:0xf
	v_cndmask_b32_dpp v201, v45, v200, vcc quad_perm:[1,0,3,2] row_mask:0xf bank_mask:0xf
	v_cndmask_b32_e32 v49, v201, v49, vcc
	v_cndmask_b32_e32 v45, v45, v201, vcc
	s_waitcnt vmcnt(20)
; #define WAIT_V(n) asm volatile("s_waitcnt vmcnt(" #n ")" ::: "memory")
;     ...
; #pragma unroll
;     for (int ai = 0; ai < 2; ++ai)
; #pragma unroll
;       for (int m = 0; m < 4; ++m)
;         epi(brow + ai * HALF + wr * 64 + m * 16 + fr, bcol + wc * 32, fq, acc[ai][0][m][0], acc[ai][0][m][1], acc[ai][1][m][0], acc[ai][1][m][1]);
;     ...
;   if (!have_next) { WAIT_V(0); __syncthreads(); }
	v_pk_add_f32 v[184:185], v[38:39], v[184:185]
	v_pk_add_f32 v[186:187], v[40:41], v[186:187]
	v_pk_add_f32 v[188:189], v[34:35], v[188:189]
	v_pk_add_f32 v[190:191], v[36:37], v[190:191]
	v_pk_add_f32 v[192:193], v[46:47], v[192:193]
	v_pk_add_f32 v[194:195], v[48:49], v[194:195]
	v_pk_add_f32 v[196:197], v[42:43], v[196:197]
	v_pk_add_f32 v[198:199], v[44:45], v[198:199]
	global_store_dwordx4 v[142:143], v[184:187], off
	global_store_dwordx4 v[144:145], v[188:191], off
	global_store_dwordx4 v[142:143], v[192:195], off offset:512
	global_store_dwordx4 v[144:145], v[196:199], off offset:512
	v_mov_b32_dpp v200, v22 quad_perm:[1,0,3,2] row_mask:0xf bank_mask:0xf
	v_cndmask_b32_dpp v201, v18, v200, vcc quad_perm:[1,0,3,2] row_mask:0xf bank_mask:0xf
	v_cndmask_b32_e32 v22, v201, v22, vcc
	v_cndmask_b32_e32 v18, v18, v201, vcc
	v_mov_b32_dpp v200, v23 quad_perm:[1,0,3,2] row_mask:0xf bank_mask:0xf
	v_cndmask_b32_dpp v201, v19, v200, vcc quad_perm:[1,0,3,2] row_mask:0xf bank_mask:0xf
	v_cndmask_b32_e32 v23, v201, v23, vcc
	v_cndmask_b32_e32 v19, v19, v201, vcc
	v_mov_b32_dpp v200, v24 quad_perm:[1,0,3,2] row_mask:0xf bank_mask:0xf
	v_cndmask_b32_dpp v201, v20, v200, vcc quad_perm:[1,0,3,2] row_mask:0xf bank_mask:0xf
	v_cndmask_b32_e32 v24, v201, v24, vcc
	v_cndmask_b32_e32 v20, v20, v201, vcc
	v_mov_b32_dpp v200, v25 quad_perm:[1,0,3,2] row_mask:0xf bank_mask:0xf
	v_cndmask_b32_dpp v201, v21, v200, vcc quad_perm:[1,0,3,2] row_mask:0xf bank_mask:0xf
	v_cndmask_b32_e32 v25, v201, v25, vcc
	v_cndmask_b32_e32 v21, v21, v201, vcc
	v_mov_b32_dpp v200, v30 quad_perm:[1,0,3,2] row_mask:0xf bank_mask:0xf
	v_cndmask_b32_dpp v201, v26, v200, vcc quad_perm:[1,0,3,2] row_mask:0xf bank_mask:0xf
	v_cndmask_b32_e32 v30, v201, v30, vcc
	v_cndmask_b32_e32 v26, v26, v201, vcc
	v_mov_b32_dpp v200, v31 quad_perm:[1,0,3,2] row_mask:0xf bank_mask:0xf
	v_cndmask_b32_dpp v201, v27, v200, vcc quad_perm:[1,0,3,2] row_mask:0xf bank_mask:0xf
	v_cndmask_b32_e32 v31, v201, v31, vcc
	v_cndmask_b32_e32 v27, v27, v201, vcc
	v_mov_b32_dpp v200, v32 quad_perm:[1,0,3,2] row_mask:0xf bank_mask:0xf
	v_cndmask_b32_dpp v201, v28, v200, vcc quad_perm:[1,0,3,2] row_mask:0xf bank_mask:0xf
	v_cndmask_b32_e32 v32, v201, v32, vcc
	v_cndmask_b32_e32 v28, v28, v201, vcc
	v_mov_b32_dpp v200, v33 quad_perm:[1,0,3,2] row_mask:0xf bank_mask:0xf
	v_cndmask_b32_dpp v201, v29, v200, vcc quad_perm:[1,0,3,2] row_mask:0xf bank_mask:0xf
	v_cndmask_b32_e32 v33, v201, v33, vcc
	v_cndmask_b32_e32 v29, v29, v201, vcc
	s_waitcnt vmcnt(16)
	v_pk_add_f32 v[220:221], v[22:23], v[220:221]
	v_pk_add_f32 v[222:223], v[24:25], v[222:223]
	v_pk_add_f32 v[224:225], v[18:19], v[224:225]
	v_pk_add_f32 v[226:227], v[20:21], v[226:227]
	v_pk_add_f32 v[228:229], v[30:31], v[228:229]
	v_pk_add_f32 v[230:231], v[32:33], v[230:231]
	v_pk_add_f32 v[232:233], v[26:27], v[232:233]
	v_pk_add_f32 v[234:235], v[28:29], v[234:235]
	global_store_dwordx4 v[146:147], v[220:223], off
	global_store_dwordx4 v[148:149], v[224:227], off
	global_store_dwordx4 v[146:147], v[228:231], off offset:512
	global_store_dwordx4 v[148:149], v[232:235], off offset:512
	v_mov_b32_dpp v200, v14 quad_perm:[1,0,3,2] row_mask:0xf bank_mask:0xf
	v_cndmask_b32_dpp v201, v6, v200, vcc quad_perm:[1,0,3,2] row_mask:0xf bank_mask:0xf
	v_cndmask_b32_e32 v14, v201, v14, vcc
	v_cndmask_b32_e32 v6, v6, v201, vcc
	v_mov_b32_dpp v200, v15 quad_perm:[1,0,3,2] row_mask:0xf bank_mask:0xf
	v_cndmask_b32_dpp v201, v7, v200, vcc quad_perm:[1,0,3,2] row_mask:0xf bank_mask:0xf
	v_cndmask_b32_e32 v15, v201, v15, vcc
	v_cndmask_b32_e32 v7, v7, v201, vcc
	v_mov_b32_dpp v200, v16 quad_perm:[1,0,3,2] row_mask:0xf bank_mask:0xf
	v_cndmask_b32_dpp v201, v8, v200, vcc quad_perm:[1,0,3,2] row_mask:0xf bank_mask:0xf
	v_cndmask_b32_e32 v16, v201, v16, vcc
	v_cndmask_b32_e32 v8, v8, v201, vcc
	v_mov_b32_dpp v200, v17 quad_perm:[1,0,3,2] row_mask:0xf bank_mask:0xf
	v_cndmask_b32_dpp v201, v9, v200, vcc quad_perm:[1,0,3,2] row_mask:0xf bank_mask:0xf
	v_cndmask_b32_e32 v17, v201, v17, vcc
	v_cndmask_b32_e32 v9, v9, v201, vcc
	v_mov_b32_dpp v200, v10 quad_perm:[1,0,3,2] row_mask:0xf bank_mask:0xf
	v_cndmask_b32_dpp v201, v2, v200, vcc quad_perm:[1,0,3,2] row_mask:0xf bank_mask:0xf
	v_cndmask_b32_e32 v10, v201, v10, vcc
	v_cndmask_b32_e32 v2, v2, v201, vcc
	v_mov_b32_dpp v200, v11 quad_perm:[1,0,3,2] row_mask:0xf bank_mask:0xf
	v_cndmask_b32_dpp v201, v3, v200, vcc quad_perm:[1,0,3,2] row_mask:0xf bank_mask:0xf
	v_cndmask_b32_e32 v11, v201, v11, vcc
	v_cndmask_b32_e32 v3, v3, v201, vcc
	v_mov_b32_dpp v200, v12 quad_perm:[1,0,3,2] row_mask:0xf bank_mask:0xf
	v_cndmask_b32_dpp v201, v4, v200, vcc quad_perm:[1,0,3,2] row_mask:0xf bank_mask:0xf
	v_cndmask_b32_e32 v12, v201, v12, vcc
	v_cndmask_b32_e32 v4, v4, v201, vcc
	v_mov_b32_dpp v200, v13 quad_perm:[1,0,3,2] row_mask:0xf bank_mask:0xf
	v_cndmask_b32_dpp v201, v5, v200, vcc quad_perm:[1,0,3,2] row_mask:0xf bank_mask:0xf
	v_cndmask_b32_e32 v13, v201, v13, vcc
	v_cndmask_b32_e32 v5, v5, v201, vcc
	s_waitcnt vmcnt(12)
	v_pk_add_f32 v[236:237], v[14:15], v[236:237]
	v_pk_add_f32 v[238:239], v[16:17], v[238:239]
	v_pk_add_f32 v[240:241], v[6:7], v[240:241]
	v_pk_add_f32 v[242:243], v[8:9], v[242:243]
	v_pk_add_f32 v[244:245], v[10:11], v[244:245]
	v_pk_add_f32 v[246:247], v[12:13], v[246:247]
	v_pk_add_f32 v[248:249], v[2:3], v[248:249]
	v_pk_add_f32 v[250:251], v[4:5], v[250:251]
	global_store_dwordx4 v[150:151], v[236:239], off
	global_store_dwordx4 v[152:153], v[240:243], off
	global_store_dwordx4 v[150:151], v[244:247], off offset:512
	global_store_dwordx4 v[152:153], v[248:251], off offset:512
	v_cmp_ne_u32_e64 s[4:5], 1, v0
	s_andn2_b64 vcc, exec, s[2:3]
	s_cbranch_vccnz .LBB0_1551
	s_waitcnt vmcnt(0)
	s_waitcnt lgkmcnt(0)
	s_barrier
	s_branch .LBB0_1551
